# v88 + attention: next K/V tile staged to the other LDS buffer between softmax and PV (placement-neutral pad)
# baseline (speedup 1.0000x reference)
.LBB0_349:
	v_exp_f32_e32 v198, v112
	v_exp_f32_e32 v199, v80
	v_exp_f32_e32 v202, v113
	v_exp_f32_e32 v203, v81
	v_exp_f32_e32 v204, v114
	v_exp_f32_e32 v205, v82
	v_exp_f32_e32 v206, v115
	v_exp_f32_e32 v207, v83
	v_exp_f32_e32 v208, v116
	v_exp_f32_e32 v209, v84
	v_exp_f32_e32 v211, v85
	v_add_f32_e32 v84, 0, v198
	v_add_f32_e32 v85, 0, v199
	v_exp_f32_e32 v210, v117
	v_add_f32_e32 v84, v202, v84
	v_add_f32_e32 v85, v203, v85
	v_exp_f32_e32 v212, v118
	v_exp_f32_e32 v213, v86
	v_add_f32_e32 v84, v204, v84
	v_add_f32_e32 v85, v205, v85
	v_exp_f32_e32 v214, v119
	v_exp_f32_e32 v215, v87
	v_add_f32_e32 v84, v206, v84
	v_add_f32_e32 v85, v207, v85
	v_exp_f32_e32 v120, v120
	v_exp_f32_e32 v216, v121
	v_exp_f32_e32 v121, v88
	v_add_f32_e32 v84, v208, v84
	v_add_f32_e32 v85, v209, v85
	v_exp_f32_e32 v217, v89
	v_add_f32_e32 v84, v210, v84
	v_add_f32_e32 v85, v211, v85
	v_exp_f32_e32 v122, v122
	v_exp_f32_e32 v218, v123
	v_exp_f32_e32 v123, v90
	v_add_f32_e32 v84, v212, v84
	v_add_f32_e32 v85, v213, v85
	v_exp_f32_e32 v219, v91
	v_add_f32_e32 v84, v214, v84
	v_add_f32_e32 v85, v215, v85
	v_exp_f32_e32 v124, v124
	v_exp_f32_e32 v220, v125
	v_add_f32_e32 v84, v120, v84
	v_add_f32_e32 v85, v121, v85
	v_exp_f32_e32 v125, v92
	v_add_f32_e32 v84, v216, v84
	v_add_f32_e32 v85, v217, v85
	v_exp_f32_e32 v221, v93
	v_exp_f32_e32 v126, v126
	v_exp_f32_e32 v222, v127
	v_add_f32_e32 v88, v122, v84
	v_add_f32_e32 v89, v123, v85
	v_exp_f32_e32 v127, v94
	v_exp_f32_e32 v223, v95
	v_exp_f32_e32 v225, v64
	v_exp_f32_e32 v227, v65
	v_add_f32_e32 v64, v218, v88
	v_add_f32_e32 v65, v219, v89
	v_exp_f32_e32 v224, v96
	v_add_f32_e32 v64, v124, v64
	v_add_f32_e32 v65, v125, v65
	v_exp_f32_e32 v226, v97
	v_add_f32_e32 v64, v220, v64
	v_add_f32_e32 v65, v221, v65
	v_exp_f32_e32 v228, v98
	v_exp_f32_e32 v229, v66
	v_add_f32_e32 v64, v126, v64
	v_add_f32_e32 v65, v127, v65
	v_exp_f32_e32 v230, v99
	v_exp_f32_e32 v231, v67
	v_add_f32_e32 v64, v222, v64
	v_add_f32_e32 v65, v223, v65
	v_exp_f32_e32 v232, v100
	v_exp_f32_e32 v233, v68
	v_add_f32_e32 v64, v224, v64
	v_add_f32_e32 v65, v225, v65
	v_exp_f32_e32 v234, v101
	v_exp_f32_e32 v235, v69
	v_add_f32_e32 v64, v226, v64
	v_add_f32_e32 v65, v227, v65
	v_exp_f32_e32 v236, v102
	v_add_f32_e32 v64, v228, v64
	v_add_f32_e32 v65, v229, v65
	v_exp_f32_e32 v237, v70
	v_exp_f32_e32 v238, v103
	v_add_f32_e32 v64, v230, v64
	v_add_f32_e32 v65, v231, v65
	v_exp_f32_e32 v239, v71
	v_exp_f32_e32 v104, v104
	v_exp_f32_e32 v240, v105
	v_add_f32_e32 v64, v232, v64
	v_add_f32_e32 v65, v233, v65
	v_exp_f32_e32 v105, v72
	v_add_f32_e32 v68, v234, v64
	v_add_f32_e32 v69, v235, v65
	v_exp_f32_e32 v241, v73
	v_exp_f32_e32 v106, v106
	v_exp_f32_e32 v242, v107
	v_exp_f32_e32 v107, v74
	v_add_f32_e32 v68, v236, v68
	v_add_f32_e32 v69, v237, v69
	v_exp_f32_e32 v243, v75
	v_add_f32_e32 v68, v238, v68
	v_add_f32_e32 v69, v239, v69
	v_exp_f32_e32 v108, v108
	v_exp_f32_e32 v244, v109
	v_exp_f32_e32 v109, v76
	v_add_f32_e32 v68, v104, v68
	v_add_f32_e32 v69, v105, v69
	v_exp_f32_e32 v245, v77
	v_add_f32_e32 v68, v240, v68
	v_add_f32_e32 v69, v241, v69
	v_exp_f32_e32 v110, v110
	v_exp_f32_e32 v246, v111
	v_exp_f32_e32 v111, v78
	v_add_f32_e32 v68, v106, v68
	v_add_f32_e32 v69, v107, v69
	v_exp_f32_e32 v247, v79
	v_add_f32_e32 v68, v242, v68
	v_add_f32_e32 v69, v243, v69
	v_cvt_pk_bf16_f32 v116, v198, v202
	v_cvt_pk_bf16_f32 v117, v204, v206
	v_cvt_pk_bf16_f32 v118, v208, v210
	v_cvt_pk_bf16_f32 v119, v212, v214
	v_cvt_pk_bf16_f32 v112, v120, v216
	s_nop 0
	v_add_f32_e32 v68, v108, v68
	v_add_f32_e32 v69, v109, v69
	v_cvt_pk_bf16_f32 v113, v122, v218
	v_cvt_pk_bf16_f32 v114, v124, v220
	v_cvt_pk_bf16_f32 v115, v126, v222
	v_cvt_pk_bf16_f32 v100, v224, v226
	v_cvt_pk_bf16_f32 v101, v228, v230
	s_nop 0
	v_add_f32_e32 v68, v244, v68
	v_add_f32_e32 v69, v245, v69
	v_cvt_pk_bf16_f32 v102, v232, v234
	v_cvt_pk_bf16_f32 v103, v236, v238
	v_cvt_pk_bf16_f32 v96, v104, v240
	v_cvt_pk_bf16_f32 v97, v106, v242
	v_cvt_pk_bf16_f32 v98, v108, v244
	s_nop 0
	v_add_f32_e32 v68, v110, v68
	v_add_f32_e32 v69, v111, v69
	v_cvt_pk_bf16_f32 v99, v110, v246
	v_cvt_pk_bf16_f32 v80, v199, v203
	v_cvt_pk_bf16_f32 v81, v205, v207
	v_cvt_pk_bf16_f32 v82, v209, v211
	v_cvt_pk_bf16_f32 v83, v213, v215
	s_nop 0
	v_add_f32_e32 v72, v246, v68
	v_add_f32_e32 v73, v247, v69
	v_cvt_pk_bf16_f32 v84, v121, v217
	v_cvt_pk_bf16_f32 v85, v123, v219
	v_cvt_pk_bf16_f32 v86, v125, v221
	v_cvt_pk_bf16_f32 v87, v127, v223
	v_cvt_pk_bf16_f32 v64, v225, v227
	s_nop 0
	v_add_f32_e32 v190, v190, v72
	v_add_f32_e32 v191, v191, v73
	v_cvt_pk_bf16_f32 v65, v229, v231
	v_cvt_pk_bf16_f32 v66, v233, v235
	v_cvt_pk_bf16_f32 v67, v237, v239
	v_cvt_pk_bf16_f32 v68, v105, v241
	v_cvt_pk_bf16_f32 v69, v107, v243
	v_cvt_pk_bf16_f32 v70, v109, v245
	v_cvt_pk_bf16_f32 v71, v111, v247
	s_cmp_ge_u32 s17, s11
	s_cbranch_scc1 .Ladw_nst
	v_xor_b32_e32 v198, 0x8000, v193
	s_waitcnt vmcnt(0)
	ds_write_b128 v198, v[164:167]
	ds_write_b128 v198, v[160:163] offset:9216
